# dn_prep stage 1: conv loads issued two tasks ahead (three register sets)
# baseline (speedup 1.0000x reference)
; #define LAS __attribute__((address_space(3)))
; __device__ __forceinline__ float lo_bf(unsigned w) { return __uint_as_float(w << 16); }
; __device__ __forceinline__ float hi_bf(unsigned w) { return __uint_as_float(w & 0xffff0000u); }
; __device__ __forceinline__ unsigned pk2(float lo, float hi) { const f32x2_t v = {lo, hi}; const bf16x2_t b = __builtin_convertvector(v, bf16x2_t); return __builtin_bit_cast(unsigned, b); }
; __device__ __forceinline__ float silu_(float x) { return x * sigm(x); }
; __device__ __forceinline__ void dn_prep_item(const Args& a, LAS unsigned char* lds, int item, int tid, int wave, int lane, int& cwh, int next_item) {
;     ...
;     for (int r = 0; r < 6; ++r) { const int task = tid + NTHR * r, which = task >> 10, i = (task & 1023) >> 4, gq = task & 15;
;         const int col = 1024 + which * 512 + h * 128 + 8 * gq;
;         v4u xv[4];
; #pragma unroll
;         for (int jj = 0; jj < 4; ++jj) { const int pos = n * 64 + i - 3 + jj; xv[jj] = (v4u){0u, 0u, 0u, 0u};
;             if (pos >= 0) xv[jj] = *(const v4u*)(P + (size_t)(b * T + pos) * NIN + col); }
;         float o[8];
; #pragma unroll
;         for (int q = 0; q < 8; ++q) o[q] = 0.f;
; #pragma unroll
;         for (int jj = 0; jj < 4; ++jj) { const v4u v = xv[jj];
;             const f32x4 w0 = *(const LAS f32x4*)(cwl + (which * 4 + jj) * 128 + 8 * gq), w1 = *(const LAS f32x4*)(cwl + (which * 4 + jj) * 128 + 8 * gq + 4);
;             o[0] += w0[0] * lo_bf(v.x); o[1] += w0[1] * hi_bf(v.x); o[2] += w0[2] * lo_bf(v.y); o[3] += w0[3] * hi_bf(v.y);
;             o[4] += w1[0] * lo_bf(v.z); o[5] += w1[1] * hi_bf(v.z); o[6] += w1[2] * lo_bf(v.w); o[7] += w1[3] * hi_bf(v.w); }
;         float s = 0.f;
; #pragma unroll
;         for (int q = 0; q < 8; ++q) { o[q] = silu_(o[q]); s += o[q] * o[q]; }
;         s += __shfl_xor(s, 1); s += __shfl_xor(s, 2); s += __shfl_xor(s, 4); s += __shfl_xor(s, 8);
;         const float inv = which == 2 ? 1.0f : rsqrtf(s + EPS) * (which == 0 ? 0.08838834764831845f : 1.0f);
;         v4u w; w.x = pk2(o[0] * inv, o[1] * inv); w.y = pk2(o[2] * inv, o[3] * inv); w.z = pk2(o[4] * inv, o[5] * inv); w.w = pk2(o[6] * inv, o[7] * inv);
;         *(LAS v4u*)(lds + (which == 0 ? L_QS : which == 1 ? L_KH : L_V) + i * KS_ + 16 * gq) = w;
.Ls1t1_760:
	s_or_b64 exec, exec, s[22:23]
	v_or_b32_e32 v2, s39, v109
	v_mov_b64_e32 v[0:1], s[10:11]
	v_mad_u64_u32 v[0:1], s[22:23], v2, s25, v[0:1]
	v_lshl_add_u64 v[0:1], v[0:1], 0, v[56:57]
	global_load_dwordx4 v[88:91], v[0:1], off
	v_add_u32_e32 v0, 0x400, v41
	v_lshrrev_b32_e32 v113, 10, v0
	v_add_u32_e32 v0, 0, v218
	v_and_b32_e32 v112, 63, v0
	v_lshl_add_u32 v1, v113, 9, v36
	v_add_u32_e32 v0, s86, v112
	v_mov_b32_e32 v120, 0
	v_cmp_lt_i32_e32 vcc, -1, v0
	v_lshlrev_b32_e32 v56, 1, v1
	v_mov_b32_e32 v128, 0
	v_mov_b32_e32 v129, 0
	v_mov_b32_e32 v130, 0
	v_mov_b32_e32 v131, 0
	s_and_saveexec_b64 s[22:23], vcc
	v_add_u32_e32 v1, s41, v0
	v_mov_b64_e32 v[2:3], s[10:11]
	v_mad_u64_u32 v[2:3], vcc, v1, s25, v[2:3]
	v_lshl_add_u64 v[2:3], v[2:3], 0, v[56:57]
	global_load_dwordx4 v[128:131], v[2:3], off
.Ls1t2_764:
	s_or_b64 exec, exec, s[22:23]
	v_cmp_lt_i32_e32 vcc, -2, v0
	v_mov_b32_e32 v121, 0
	v_mov_b32_e32 v122, 0
	v_mov_b32_e32 v123, 0
	s_and_saveexec_b64 s[22:23], vcc
	v_add_u32_e32 v1, s42, v0
	v_mov_b64_e32 v[2:3], s[10:11]
	v_mad_u64_u32 v[2:3], vcc, v1, s25, v[2:3]
	v_lshl_add_u64 v[2:3], v[2:3], 0, v[56:57]
	global_load_dwordx4 v[120:123], v[2:3], off
.Ls1t2_766:
	s_or_b64 exec, exec, s[22:23]
	v_cmp_lt_i32_e32 vcc, -3, v0
	v_mov_b32_e32 v132, 0
	v_mov_b32_e32 v133, 0
	v_mov_b32_e32 v134, 0
	v_mov_b32_e32 v135, 0
	s_and_saveexec_b64 s[22:23], vcc
	v_add_u32_e32 v2, s43, v0
	v_mov_b64_e32 v[0:1], s[10:11]
	v_mad_u64_u32 v[0:1], vcc, v2, s25, v[0:1]
	v_lshl_add_u64 v[0:1], v[0:1], 0, v[56:57]
	global_load_dwordx4 v[132:135], v[0:1], off
; #define LAS __attribute__((address_space(3)))
; __device__ __forceinline__ float lo_bf(unsigned w) { return __uint_as_float(w << 16); }
; __device__ __forceinline__ float hi_bf(unsigned w) { return __uint_as_float(w & 0xffff0000u); }
; __device__ __forceinline__ unsigned pk2(float lo, float hi) { const f32x2_t v = {lo, hi}; const bf16x2_t b = __builtin_convertvector(v, bf16x2_t); return __builtin_bit_cast(unsigned, b); }
; __device__ __forceinline__ float silu_(float x) { return x * sigm(x); }
; __device__ __forceinline__ void dn_prep_item(const Args& a, LAS unsigned char* lds, int item, int tid, int wave, int lane, int& cwh, int next_item) {
;     ...
;     for (int r = 0; r < 6; ++r) { const int task = tid + NTHR * r, which = task >> 10, i = (task & 1023) >> 4, gq = task & 15;
;         const int col = 1024 + which * 512 + h * 128 + 8 * gq;
;         v4u xv[4];
; #pragma unroll
;         for (int jj = 0; jj < 4; ++jj) { const int pos = n * 64 + i - 3 + jj; xv[jj] = (v4u){0u, 0u, 0u, 0u};
;             if (pos >= 0) xv[jj] = *(const v4u*)(P + (size_t)(b * T + pos) * NIN + col); }
;         float o[8];
; #pragma unroll
;         for (int q = 0; q < 8; ++q) o[q] = 0.f;
; #pragma unroll
;         for (int jj = 0; jj < 4; ++jj) { const v4u v = xv[jj];
;             const f32x4 w0 = *(const LAS f32x4*)(cwl + (which * 4 + jj) * 128 + 8 * gq), w1 = *(const LAS f32x4*)(cwl + (which * 4 + jj) * 128 + 8 * gq + 4);
;             o[0] += w0[0] * lo_bf(v.x); o[1] += w0[1] * hi_bf(v.x); o[2] += w0[2] * lo_bf(v.y); o[3] += w0[3] * hi_bf(v.y);
;             o[4] += w1[0] * lo_bf(v.z); o[5] += w1[1] * hi_bf(v.z); o[6] += w1[2] * lo_bf(v.w); o[7] += w1[3] * hi_bf(v.w); }
;         float s = 0.f;
; #pragma unroll
;         for (int q = 0; q < 8; ++q) { o[q] = silu_(o[q]); s += o[q] * o[q]; }
;         s += __shfl_xor(s, 1); s += __shfl_xor(s, 2); s += __shfl_xor(s, 4); s += __shfl_xor(s, 8);
;         const float inv = which == 2 ? 1.0f : rsqrtf(s + EPS) * (which == 0 ? 0.08838834764831845f : 1.0f);
;         v4u w; w.x = pk2(o[0] * inv, o[1] * inv); w.y = pk2(o[2] * inv, o[3] * inv); w.z = pk2(o[4] * inv, o[5] * inv); w.w = pk2(o[6] * inv, o[7] * inv);
;         *(LAS v4u*)(lds + (which == 0 ? L_QS : which == 1 ? L_KH : L_V) + i * KS_ + 16 * gq) = w;
.Ls1t2_768:
	s_or_b64 exec, exec, s[22:23]
	v_or_b32_e32 v2, s39, v112
	v_mov_b64_e32 v[0:1], s[10:11]
	v_mad_u64_u32 v[0:1], s[22:23], v2, s25, v[0:1]
	v_lshl_add_u64 v[0:1], v[0:1], 0, v[56:57]
	global_load_dwordx4 v[116:119], v[0:1], off
	v_lshl_add_u32 v0, v43, 11, v150
	ds_read_b128 v[44:47], v0
	ds_read_b128 v[28:31], v0 offset:16
	ds_read_b128 v[72:75], v0 offset:512
	ds_read_b128 v[24:27], v0 offset:528
	ds_read_b128 v[76:79], v0 offset:1024
	ds_read_b128 v[12:15], v0 offset:1040
	ds_read_b128 v[80:83], v0 offset:1536
	ds_read_b128 v[0:3], v0 offset:1552
	s_waitcnt vmcnt(11)
	v_lshlrev_b32_e32 v32, 16, v16
	v_and_b32_e32 v33, 0xffff0000, v16
	s_waitcnt lgkmcnt(0)
	v_pk_fma_f32 v[32:33], v[44:45], v[32:33], 0 op_sel_hi:[1,1,0]
	s_waitcnt vmcnt(10)
	v_lshlrev_b32_e32 v34, 16, v8
	v_and_b32_e32 v35, 0xffff0000, v8
	v_pk_fma_f32 v[32:33], v[72:73], v[34:35], v[32:33]
	s_waitcnt vmcnt(9)
	v_lshlrev_b32_e32 v34, 16, v20
	v_and_b32_e32 v35, 0xffff0000, v20
	v_pk_fma_f32 v[32:33], v[76:77], v[34:35], v[32:33]
	v_lshlrev_b32_e32 v16, 16, v17
	v_and_b32_e32 v17, 0xffff0000, v17
	v_pk_fma_f32 v[16:17], v[46:47], v[16:17], 0 op_sel_hi:[1,1,0]
	v_lshlrev_b32_e32 v20, 16, v18
	v_cmp_ne_u32_e32 vcc, 2, v43
	s_waitcnt vmcnt(8)
	v_lshlrev_b32_e32 v34, 16, v4
	v_and_b32_e32 v35, 0xffff0000, v4
	v_pk_fma_f32 v[32:33], v[80:81], v[34:35], v[32:33]
	s_nop 0
	v_mul_f32_e32 v4, 0xbfb8aa3b, v32
	v_exp_f32_e32 v8, v4
	v_mov_b32_e32 v4, 1.0
	v_add_f32_e32 v8, 1.0, v8
	v_rcp_f32_e32 v34, v8
	v_mul_f32_e32 v8, 0xbfb8aa3b, v33
	v_exp_f32_e32 v8, v8
	s_nop 0
	v_add_f32_e32 v8, 1.0, v8
	v_rcp_f32_e32 v35, v8
	v_lshlrev_b32_e32 v8, 16, v9
	v_and_b32_e32 v9, 0xffff0000, v9
	v_pk_fma_f32 v[8:9], v[74:75], v[8:9], v[16:17]
	v_lshlrev_b32_e32 v16, 16, v21
	v_and_b32_e32 v17, 0xffff0000, v21
	v_pk_fma_f32 v[8:9], v[78:79], v[16:17], v[8:9]
	v_lshlrev_b32_e32 v16, 16, v5
	v_and_b32_e32 v17, 0xffff0000, v5
	v_pk_fma_f32 v[8:9], v[82:83], v[16:17], v[8:9]
	v_and_b32_e32 v21, 0xffff0000, v18
	v_mul_f32_e32 v5, 0xbfb8aa3b, v8
	v_exp_f32_e32 v5, v5
	v_pk_fma_f32 v[20:21], v[28:29], v[20:21], 0 op_sel_hi:[1,1,0]
	v_lshlrev_b32_e32 v28, 16, v10
	v_and_b32_e32 v29, 0xffff0000, v10
	v_add_f32_e32 v5, 1.0, v5
	v_rcp_f32_e32 v16, v5
	v_mul_f32_e32 v5, 0xbfb8aa3b, v9
	v_exp_f32_e32 v5, v5
	v_pk_fma_f32 v[20:21], v[24:25], v[28:29], v[20:21]
	v_lshlrev_b32_e32 v24, 16, v22
	v_and_b32_e32 v25, 0xffff0000, v22
	v_pk_fma_f32 v[12:13], v[12:13], v[24:25], v[20:21]
	v_lshlrev_b32_e32 v20, 16, v6
	v_and_b32_e32 v21, 0xffff0000, v6
	v_add_f32_e32 v5, 1.0, v5
	v_pk_fma_f32 v[0:1], v[0:1], v[20:21], v[12:13]
	v_rcp_f32_e32 v17, v5
	v_mul_f32_e32 v5, 0xbfb8aa3b, v0
	v_exp_f32_e32 v5, v5
	v_lshlrev_b32_e32 v18, 16, v19
	v_and_b32_e32 v19, 0xffff0000, v19
	v_pk_fma_f32 v[18:19], v[30:31], v[18:19], 0 op_sel_hi:[1,1,0]
	v_add_f32_e32 v5, 1.0, v5
	v_rcp_f32_e32 v12, v5
	v_mul_f32_e32 v5, 0xbfb8aa3b, v1
	v_exp_f32_e32 v5, v5
	v_lshlrev_b32_e32 v10, 16, v11
	v_and_b32_e32 v11, 0xffff0000, v11
	v_pk_fma_f32 v[10:11], v[26:27], v[10:11], v[18:19]
	v_lshlrev_b32_e32 v18, 16, v23
	v_and_b32_e32 v19, 0xffff0000, v23
	v_pk_fma_f32 v[10:11], v[14:15], v[18:19], v[10:11]
	v_lshlrev_b32_e32 v6, 16, v7
	v_and_b32_e32 v7, 0xffff0000, v7
	v_add_f32_e32 v5, 1.0, v5
	v_pk_fma_f32 v[2:3], v[2:3], v[6:7], v[10:11]
	v_rcp_f32_e32 v13, v5
	v_mul_f32_e32 v5, 0xbfb8aa3b, v2
	v_exp_f32_e32 v5, v5
	v_pk_mul_f32 v[32:33], v[32:33], v[34:35]
	v_pk_mul_f32 v[8:9], v[8:9], v[16:17]
	v_pk_mul_f32 v[34:35], v[32:33], v[32:33]
	v_add_f32_e32 v5, 1.0, v5
	v_rcp_f32_e32 v6, v5
	v_mul_f32_e32 v5, 0xbfb8aa3b, v3
	v_exp_f32_e32 v5, v5
	v_pk_mul_f32 v[16:17], v[8:9], v[8:9]
	v_pk_mul_f32 v[0:1], v[0:1], v[12:13]
	v_add_f32_e32 v5, 1.0, v5
	v_rcp_f32_e32 v7, v5
	v_add_f32_e32 v5, v34, v35
	v_add_f32_e32 v5, v16, v5
	v_pk_mul_f32 v[12:13], v[0:1], v[0:1]
	v_add_f32_e32 v5, v17, v5
	v_pk_mul_f32 v[2:3], v[2:3], v[6:7]
	v_add_f32_e32 v5, v12, v5
	v_pk_mul_f32 v[6:7], v[2:3], v[2:3]
	v_add_f32_e32 v5, v13, v5
	v_add_f32_e32 v5, v6, v5
	v_add_f32_e32 v5, v7, v5
	ds_bpermute_b32 v6, v37, v5
	s_waitcnt lgkmcnt(0)
	v_add_f32_e32 v5, v5, v6
	ds_bpermute_b32 v6, v38, v5
	s_waitcnt lgkmcnt(0)
	v_add_f32_e32 v5, v5, v6
	ds_bpermute_b32 v6, v39, v5
	s_waitcnt lgkmcnt(0)
	v_add_f32_e32 v5, v5, v6
	ds_bpermute_b32 v6, v40, v5
	s_and_saveexec_b64 s[22:23], vcc
	s_cbranch_execz .Ls1t0_754
	s_waitcnt lgkmcnt(0)
	v_add_f32_e32 v4, v5, v6
	v_add_f32_e32 v4, 0x358637bd, v4
	v_mul_f32_e32 v5, 0x4b800000, v4
	v_cmp_gt_f32_e32 vcc, s34, v4
	s_nop 1
	v_cndmask_b32_e32 v4, v4, v5, vcc
	v_rsq_f32_e32 v4, v4
	s_nop 0
	v_mul_f32_e32 v5, 0x45800000, v4
	v_cndmask_b32_e32 v4, v4, v5, vcc
	v_cmp_gt_u32_e32 vcc, s30, v41
	s_nop 1
	v_cndmask_b32_e32 v5, 1.0, v231, vcc
	v_mul_f32_e32 v4, v5, v4
.Ls1t0_754:
	s_or_b64 exec, exec, s[22:23]
	v_pk_mul_f32 v[0:1], v[0:1], v[4:5] op_sel_hi:[1,0]
	v_cmp_eq_u32_e32 vcc, 1, v43
	v_cvt_pk_bf16_f32 v12, v0, v1
	v_pk_mul_f32 v[0:1], v[2:3], v[4:5] op_sel_hi:[1,0]
	s_waitcnt lgkmcnt(0)
	v_pk_mul_f32 v[6:7], v[32:33], v[4:5] op_sel_hi:[1,0]
	v_cvt_pk_bf16_f32 v13, v0, v1
	v_cndmask_b32_e64 v0, v188, 0, vcc
	v_cmp_lt_u32_e32 vcc, s31, v41
	v_cvt_pk_bf16_f32 v10, v6, v7
	v_pk_mul_f32 v[6:7], v[8:9], v[4:5] op_sel_hi:[1,0]
	v_cndmask_b32_e32 v0, v232, v0, vcc
	v_add_u32_e32 v0, 0, v0
	v_mul_u32_u24_e32 v1, 0x110, v42
	v_cvt_pk_bf16_f32 v11, v6, v7
	v_add3_u32 v0, v0, v1, v151
	ds_write_b128 v0, v[10:13]
	v_add_u32_e32 v111, 0x600, v41
	v_add_u32_e32 v0, 0x60, v220
	v_lshrrev_b32_e32 v43, 10, v111
	v_and_b32_e32 v42, 63, v0
	v_lshl_add_u32 v1, v43, 9, v36
	v_add_u32_e32 v0, s86, v42
	v_cmp_lt_i32_e32 vcc, -1, v0
	v_mov_b32_e32 v8, 0
	v_lshlrev_b32_e32 v56, 1, v1
	v_mov_b32_e32 v16, 0
	v_mov_b32_e32 v17, 0
	v_mov_b32_e32 v18, 0
	v_mov_b32_e32 v19, 0
	s_and_saveexec_b64 s[22:23], vcc
	v_add_u32_e32 v1, s41, v0
	v_mov_b64_e32 v[2:3], s[10:11]
	v_mad_u64_u32 v[2:3], vcc, v1, s25, v[2:3]
	v_lshl_add_u64 v[2:3], v[2:3], 0, v[56:57]
	global_load_dwordx4 v[16:19], v[2:3], off

; #define LAS __attribute__((address_space(3)))
; __device__ __forceinline__ float lo_bf(unsigned w) { return __uint_as_float(w << 16); }
; __device__ __forceinline__ float hi_bf(unsigned w) { return __uint_as_float(w & 0xffff0000u); }
; __device__ __forceinline__ unsigned pk2(float lo, float hi) { const f32x2_t v = {lo, hi}; const bf16x2_t b = __builtin_convertvector(v, bf16x2_t); return __builtin_bit_cast(unsigned, b); }
; __device__ __forceinline__ float silu_(float x) { return x * sigm(x); }
; __device__ __forceinline__ void dn_prep_item(const Args& a, LAS unsigned char* lds, int item, int tid, int wave, int lane, int& cwh, int next_item) {
;     ...
;     for (int r = 0; r < 6; ++r) { const int task = tid + NTHR * r, which = task >> 10, i = (task & 1023) >> 4, gq = task & 15;
;         const int col = 1024 + which * 512 + h * 128 + 8 * gq;
;         v4u xv[4];
; #pragma unroll
;         for (int jj = 0; jj < 4; ++jj) { const int pos = n * 64 + i - 3 + jj; xv[jj] = (v4u){0u, 0u, 0u, 0u};
;             if (pos >= 0) xv[jj] = *(const v4u*)(P + (size_t)(b * T + pos) * NIN + col); }
;         float o[8];
; #pragma unroll
;         for (int q = 0; q < 8; ++q) o[q] = 0.f;
; #pragma unroll
;         for (int jj = 0; jj < 4; ++jj) { const v4u v = xv[jj];
;             const f32x4 w0 = *(const LAS f32x4*)(cwl + (which * 4 + jj) * 128 + 8 * gq), w1 = *(const LAS f32x4*)(cwl + (which * 4 + jj) * 128 + 8 * gq + 4);
;             o[0] += w0[0] * lo_bf(v.x); o[1] += w0[1] * hi_bf(v.x); o[2] += w0[2] * lo_bf(v.y); o[3] += w0[3] * hi_bf(v.y);
;             o[4] += w1[0] * lo_bf(v.z); o[5] += w1[1] * hi_bf(v.z); o[6] += w1[2] * lo_bf(v.w); o[7] += w1[3] * hi_bf(v.w); }
;         float s = 0.f;
; #pragma unroll
;         for (int q = 0; q < 8; ++q) { o[q] = silu_(o[q]); s += o[q] * o[q]; }
;         s += __shfl_xor(s, 1); s += __shfl_xor(s, 2); s += __shfl_xor(s, 4); s += __shfl_xor(s, 8);
;         const float inv = which == 2 ? 1.0f : rsqrtf(s + EPS) * (which == 0 ? 0.08838834764831845f : 1.0f);
;         v4u w; w.x = pk2(o[0] * inv, o[1] * inv); w.y = pk2(o[2] * inv, o[3] * inv); w.z = pk2(o[4] * inv, o[5] * inv); w.w = pk2(o[6] * inv, o[7] * inv);
;         *(LAS v4u*)(lds + (which == 0 ? L_QS : which == 1 ? L_KH : L_V) + i * KS_ + 16 * gq) = w;
.Ls1t3_752:
	s_or_b64 exec, exec, s[22:23]
	v_or_b32_e32 v2, s39, v42
	v_mov_b64_e32 v[0:1], s[10:11]
	v_mad_u64_u32 v[0:1], s[22:23], v2, s25, v[0:1]
	v_lshl_add_u64 v[0:1], v[0:1], 0, v[56:57]
	global_load_dwordx4 v[4:7], v[0:1], off
	v_lshl_add_u32 v0, v110, 11, v150
	ds_read_b128 v[72:75], v0
	ds_read_b128 v[28:31], v0 offset:16
	ds_read_b128 v[76:79], v0 offset:512
	ds_read_b128 v[24:27], v0 offset:528
	ds_read_b128 v[80:83], v0 offset:1024
	ds_read_b128 v[96:99], v0 offset:1040
	ds_read_b128 v[84:87], v0 offset:1536
	ds_read_b128 v[0:3], v0 offset:1552
	s_waitcnt vmcnt(11)
	v_lshlrev_b32_e32 v32, 16, v100
	v_and_b32_e32 v33, 0xffff0000, v100
	s_waitcnt lgkmcnt(7)
	v_pk_fma_f32 v[32:33], v[72:73], v[32:33], 0 op_sel_hi:[1,1,0]
	s_waitcnt vmcnt(10)
	v_lshlrev_b32_e32 v34, 16, v92
	v_and_b32_e32 v35, 0xffff0000, v92
	s_waitcnt lgkmcnt(5)
	v_pk_fma_f32 v[32:33], v[76:77], v[34:35], v[32:33]
	s_waitcnt vmcnt(9)
	v_lshlrev_b32_e32 v34, 16, v104
	v_and_b32_e32 v35, 0xffff0000, v104
	s_waitcnt lgkmcnt(3)
	v_pk_fma_f32 v[32:33], v[80:81], v[34:35], v[32:33]
	v_lshlrev_b32_e32 v100, 16, v101
	v_and_b32_e32 v101, 0xffff0000, v101
	v_pk_fma_f32 v[100:101], v[74:75], v[100:101], 0 op_sel_hi:[1,1,0]
	v_lshlrev_b32_e32 v104, 16, v102
	v_cmp_ne_u32_e32 vcc, 2, v110
	s_waitcnt vmcnt(8)
	v_lshlrev_b32_e32 v34, 16, v88
	v_and_b32_e32 v35, 0xffff0000, v88
	s_waitcnt lgkmcnt(1)
	v_pk_fma_f32 v[32:33], v[84:85], v[34:35], v[32:33]
	s_nop 0
	v_mul_f32_e32 v88, 0xbfb8aa3b, v32
	v_exp_f32_e32 v92, v88
	v_mov_b32_e32 v88, 1.0
	v_add_f32_e32 v92, 1.0, v92
	v_rcp_f32_e32 v34, v92
	v_mul_f32_e32 v92, 0xbfb8aa3b, v33
	v_exp_f32_e32 v92, v92
	s_nop 0
	v_add_f32_e32 v92, 1.0, v92
	v_rcp_f32_e32 v35, v92
	v_lshlrev_b32_e32 v92, 16, v93
	v_and_b32_e32 v93, 0xffff0000, v93
	v_pk_fma_f32 v[92:93], v[78:79], v[92:93], v[100:101]
	v_lshlrev_b32_e32 v100, 16, v105
	v_and_b32_e32 v101, 0xffff0000, v105
	v_pk_fma_f32 v[92:93], v[82:83], v[100:101], v[92:93]
	v_lshlrev_b32_e32 v100, 16, v89
	v_and_b32_e32 v101, 0xffff0000, v89
	v_pk_fma_f32 v[92:93], v[86:87], v[100:101], v[92:93]
	v_and_b32_e32 v105, 0xffff0000, v102
	v_mul_f32_e32 v89, 0xbfb8aa3b, v92
	v_exp_f32_e32 v89, v89
	v_pk_fma_f32 v[104:105], v[28:29], v[104:105], 0 op_sel_hi:[1,1,0]
	v_lshlrev_b32_e32 v28, 16, v94
	v_and_b32_e32 v29, 0xffff0000, v94
	v_add_f32_e32 v89, 1.0, v89
	v_rcp_f32_e32 v100, v89
	v_mul_f32_e32 v89, 0xbfb8aa3b, v93
	v_exp_f32_e32 v89, v89
	v_pk_fma_f32 v[104:105], v[24:25], v[28:29], v[104:105]
	v_lshlrev_b32_e32 v24, 16, v106
	v_and_b32_e32 v25, 0xffff0000, v106
	v_pk_fma_f32 v[96:97], v[96:97], v[24:25], v[104:105]
	v_lshlrev_b32_e32 v104, 16, v90
	v_and_b32_e32 v105, 0xffff0000, v90
	v_add_f32_e32 v89, 1.0, v89
	s_waitcnt lgkmcnt(0)
	v_pk_fma_f32 v[0:1], v[0:1], v[104:105], v[96:97]
	v_rcp_f32_e32 v101, v89
	v_mul_f32_e32 v89, 0xbfb8aa3b, v0
	v_exp_f32_e32 v89, v89
	v_lshlrev_b32_e32 v102, 16, v103
	v_and_b32_e32 v103, 0xffff0000, v103
	v_pk_fma_f32 v[102:103], v[30:31], v[102:103], 0 op_sel_hi:[1,1,0]
	v_add_f32_e32 v89, 1.0, v89
	v_rcp_f32_e32 v96, v89
	v_mul_f32_e32 v89, 0xbfb8aa3b, v1
	v_exp_f32_e32 v89, v89
	v_lshlrev_b32_e32 v94, 16, v95
	v_and_b32_e32 v95, 0xffff0000, v95
	v_pk_fma_f32 v[94:95], v[26:27], v[94:95], v[102:103]
	v_lshlrev_b32_e32 v102, 16, v107
	v_and_b32_e32 v103, 0xffff0000, v107
	v_pk_fma_f32 v[94:95], v[98:99], v[102:103], v[94:95]
	v_lshlrev_b32_e32 v90, 16, v91
	v_and_b32_e32 v91, 0xffff0000, v91
	v_add_f32_e32 v89, 1.0, v89
	v_pk_fma_f32 v[2:3], v[2:3], v[90:91], v[94:95]
	v_rcp_f32_e32 v97, v89
	v_mul_f32_e32 v89, 0xbfb8aa3b, v2
	v_exp_f32_e32 v89, v89
	v_pk_mul_f32 v[32:33], v[32:33], v[34:35]
	v_pk_mul_f32 v[92:93], v[92:93], v[100:101]
	v_pk_mul_f32 v[34:35], v[32:33], v[32:33]
	v_add_f32_e32 v89, 1.0, v89
	v_rcp_f32_e32 v90, v89
	v_mul_f32_e32 v89, 0xbfb8aa3b, v3
	v_exp_f32_e32 v89, v89
	v_pk_mul_f32 v[100:101], v[92:93], v[92:93]
	v_pk_mul_f32 v[0:1], v[0:1], v[96:97]
	v_add_f32_e32 v89, 1.0, v89
	v_rcp_f32_e32 v91, v89
	v_add_f32_e32 v89, v34, v35
	v_add_f32_e32 v89, v100, v89
	v_pk_mul_f32 v[96:97], v[0:1], v[0:1]
	v_add_f32_e32 v89, v101, v89
	v_pk_mul_f32 v[2:3], v[2:3], v[90:91]
	v_add_f32_e32 v89, v96, v89
	v_pk_mul_f32 v[90:91], v[2:3], v[2:3]
	v_add_f32_e32 v89, v97, v89
	v_add_f32_e32 v89, v90, v89
	v_add_f32_e32 v89, v91, v89
	ds_bpermute_b32 v90, v37, v89
	s_waitcnt lgkmcnt(0)
	v_add_f32_e32 v89, v89, v90
	ds_bpermute_b32 v90, v38, v89
	s_waitcnt lgkmcnt(0)
	v_add_f32_e32 v89, v89, v90
	ds_bpermute_b32 v90, v39, v89
	s_waitcnt lgkmcnt(0)
	v_add_f32_e32 v89, v89, v90
	ds_bpermute_b32 v90, v40, v89
	s_and_saveexec_b64 s[22:23], vcc
	s_cbranch_execz .Ls1t1_762
	s_waitcnt lgkmcnt(0)
	v_add_f32_e32 v88, v89, v90
	v_add_f32_e32 v88, 0x358637bd, v88
	v_mul_f32_e32 v89, 0x4b800000, v88
	v_cmp_gt_f32_e32 vcc, s34, v88
	s_nop 1
	v_cndmask_b32_e32 v88, v88, v89, vcc
	v_rsq_f32_e32 v88, v88
	s_nop 0
	v_mul_f32_e32 v89, 0x45800000, v88
	v_cndmask_b32_e32 v88, v88, v89, vcc
	v_cmp_gt_u32_e32 vcc, s30, v108
	s_nop 1
	v_cndmask_b32_e32 v89, 1.0, v231, vcc
	v_mul_f32_e32 v88, v89, v88
.Ls1t1_762:
	s_or_b64 exec, exec, s[22:23]
	v_pk_mul_f32 v[0:1], v[0:1], v[88:89] op_sel_hi:[1,0]
	v_cmp_eq_u32_e32 vcc, 1, v110
	v_cvt_pk_bf16_f32 v96, v0, v1
	v_pk_mul_f32 v[0:1], v[2:3], v[88:89] op_sel_hi:[1,0]
	s_waitcnt lgkmcnt(0)
	v_pk_mul_f32 v[90:91], v[32:33], v[88:89] op_sel_hi:[1,0]
	v_cvt_pk_bf16_f32 v97, v0, v1
	v_cndmask_b32_e64 v0, v188, 0, vcc
	v_cmp_lt_u32_e32 vcc, s31, v108
	v_cvt_pk_bf16_f32 v94, v90, v91
	v_pk_mul_f32 v[90:91], v[92:93], v[88:89] op_sel_hi:[1,0]
	v_cndmask_b32_e32 v0, v232, v0, vcc
	v_add_u32_e32 v0, 0, v0
	v_mul_u32_u24_e32 v1, 0x110, v109
	v_cvt_pk_bf16_f32 v95, v90, v91
	v_add3_u32 v0, v0, v1, v151
	ds_write_b128 v0, v[94:97]
	v_add_u32_e32 v108, 0x200, v111
	v_add_u32_e32 v0, 0x60, v219
	v_lshrrev_b32_e32 v110, 10, v108
	v_and_b32_e32 v109, 63, v0
	v_lshl_add_u32 v1, v110, 9, v36
	v_add_u32_e32 v0, s86, v109
	v_mov_b32_e32 v92, 0
	v_cmp_lt_i32_e32 vcc, -1, v0
	v_lshlrev_b32_e32 v56, 1, v1
	v_mov_b32_e32 v100, 0
	v_mov_b32_e32 v101, 0
	v_mov_b32_e32 v102, 0
	v_mov_b32_e32 v103, 0
	s_and_saveexec_b64 s[22:23], vcc
	v_add_u32_e32 v1, s41, v0
	v_mov_b64_e32 v[2:3], s[10:11]
	v_mad_u64_u32 v[2:3], vcc, v1, s25, v[2:3]
	v_lshl_add_u64 v[2:3], v[2:3], 0, v[56:57]
	global_load_dwordx4 v[100:103], v[2:3], off

; #define LAS __attribute__((address_space(3)))
; __device__ __forceinline__ float lo_bf(unsigned w) { return __uint_as_float(w << 16); }
; __device__ __forceinline__ float hi_bf(unsigned w) { return __uint_as_float(w & 0xffff0000u); }
; __device__ __forceinline__ unsigned pk2(float lo, float hi) { const f32x2_t v = {lo, hi}; const bf16x2_t b = __builtin_convertvector(v, bf16x2_t); return __builtin_bit_cast(unsigned, b); }
; __device__ __forceinline__ float silu_(float x) { return x * sigm(x); }
; __device__ __forceinline__ void dn_prep_item(const Args& a, LAS unsigned char* lds, int item, int tid, int wave, int lane, int& cwh, int next_item) {
;     ...
;     for (int r = 0; r < 6; ++r) { const int task = tid + NTHR * r, which = task >> 10, i = (task & 1023) >> 4, gq = task & 15;
;         const int col = 1024 + which * 512 + h * 128 + 8 * gq;
;         v4u xv[4];
; #pragma unroll
;         for (int jj = 0; jj < 4; ++jj) { const int pos = n * 64 + i - 3 + jj; xv[jj] = (v4u){0u, 0u, 0u, 0u};
;             if (pos >= 0) xv[jj] = *(const v4u*)(P + (size_t)(b * T + pos) * NIN + col); }
;         float o[8];
; #pragma unroll
;         for (int q = 0; q < 8; ++q) o[q] = 0.f;
; #pragma unroll
;         for (int jj = 0; jj < 4; ++jj) { const v4u v = xv[jj];
;             const f32x4 w0 = *(const LAS f32x4*)(cwl + (which * 4 + jj) * 128 + 8 * gq), w1 = *(const LAS f32x4*)(cwl + (which * 4 + jj) * 128 + 8 * gq + 4);
;             o[0] += w0[0] * lo_bf(v.x); o[1] += w0[1] * hi_bf(v.x); o[2] += w0[2] * lo_bf(v.y); o[3] += w0[3] * hi_bf(v.y);
;             o[4] += w1[0] * lo_bf(v.z); o[5] += w1[1] * hi_bf(v.z); o[6] += w1[2] * lo_bf(v.w); o[7] += w1[3] * hi_bf(v.w); }
;         float s = 0.f;
; #pragma unroll
;         for (int q = 0; q < 8; ++q) { o[q] = silu_(o[q]); s += o[q] * o[q]; }
;         s += __shfl_xor(s, 1); s += __shfl_xor(s, 2); s += __shfl_xor(s, 4); s += __shfl_xor(s, 8);
;         const float inv = which == 2 ? 1.0f : rsqrtf(s + EPS) * (which == 0 ? 0.08838834764831845f : 1.0f);
;         v4u w; w.x = pk2(o[0] * inv, o[1] * inv); w.y = pk2(o[2] * inv, o[3] * inv); w.z = pk2(o[4] * inv, o[5] * inv); w.w = pk2(o[6] * inv, o[7] * inv);
;         *(LAS v4u*)(lds + (which == 0 ? L_QS : which == 1 ? L_KH : L_V) + i * KS_ + 16 * gq) = w;
.Ls1t4_760:
	s_or_b64 exec, exec, s[22:23]
	v_or_b32_e32 v2, s39, v109
	v_mov_b64_e32 v[0:1], s[10:11]
	v_mad_u64_u32 v[0:1], s[22:23], v2, s25, v[0:1]
	v_lshl_add_u64 v[0:1], v[0:1], 0, v[56:57]
	global_load_dwordx4 v[88:91], v[0:1], off
	v_lshl_add_u32 v0, v113, 11, v150
	ds_read_b128 v[44:47], v0
	ds_read_b128 v[28:31], v0 offset:16
	ds_read_b128 v[72:75], v0 offset:512
	ds_read_b128 v[24:27], v0 offset:528
	ds_read_b128 v[76:79], v0 offset:1024
	ds_read_b128 v[124:127], v0 offset:1040
	ds_read_b128 v[80:83], v0 offset:1536
	ds_read_b128 v[0:3], v0 offset:1552
	s_waitcnt vmcnt(11)
	v_lshlrev_b32_e32 v32, 16, v128
	v_and_b32_e32 v33, 0xffff0000, v128
	s_waitcnt lgkmcnt(7)
	v_pk_fma_f32 v[32:33], v[44:45], v[32:33], 0 op_sel_hi:[1,1,0]
	s_waitcnt vmcnt(10)
	v_lshlrev_b32_e32 v34, 16, v120
	v_and_b32_e32 v35, 0xffff0000, v120
	s_waitcnt lgkmcnt(5)
	v_pk_fma_f32 v[32:33], v[72:73], v[34:35], v[32:33]
	s_waitcnt vmcnt(9)
	v_lshlrev_b32_e32 v34, 16, v132
	v_and_b32_e32 v35, 0xffff0000, v132
	s_waitcnt lgkmcnt(3)
	v_pk_fma_f32 v[32:33], v[76:77], v[34:35], v[32:33]
	v_lshlrev_b32_e32 v128, 16, v129
	v_and_b32_e32 v129, 0xffff0000, v129
	v_pk_fma_f32 v[128:129], v[46:47], v[128:129], 0 op_sel_hi:[1,1,0]
	v_lshlrev_b32_e32 v132, 16, v130
	v_cmp_ne_u32_e32 vcc, 2, v113
	s_waitcnt vmcnt(8)
	v_lshlrev_b32_e32 v34, 16, v116
	v_and_b32_e32 v35, 0xffff0000, v116
	s_waitcnt lgkmcnt(1)
	v_pk_fma_f32 v[32:33], v[80:81], v[34:35], v[32:33]
	s_nop 0
	v_mul_f32_e32 v116, 0xbfb8aa3b, v32
	v_exp_f32_e32 v120, v116
	v_mov_b32_e32 v116, 1.0
	v_add_f32_e32 v120, 1.0, v120
	v_rcp_f32_e32 v34, v120
	v_mul_f32_e32 v120, 0xbfb8aa3b, v33
	v_exp_f32_e32 v120, v120
	s_nop 0
	v_add_f32_e32 v120, 1.0, v120
	v_rcp_f32_e32 v35, v120
	v_lshlrev_b32_e32 v120, 16, v121
	v_and_b32_e32 v121, 0xffff0000, v121
	v_pk_fma_f32 v[120:121], v[74:75], v[120:121], v[128:129]
	v_lshlrev_b32_e32 v128, 16, v133
	v_and_b32_e32 v129, 0xffff0000, v133
	v_pk_fma_f32 v[120:121], v[78:79], v[128:129], v[120:121]
	v_lshlrev_b32_e32 v128, 16, v117
	v_and_b32_e32 v129, 0xffff0000, v117
	v_pk_fma_f32 v[120:121], v[82:83], v[128:129], v[120:121]
	v_and_b32_e32 v133, 0xffff0000, v130
	v_mul_f32_e32 v117, 0xbfb8aa3b, v120
	v_exp_f32_e32 v117, v117
	v_pk_fma_f32 v[132:133], v[28:29], v[132:133], 0 op_sel_hi:[1,1,0]
	v_lshlrev_b32_e32 v28, 16, v122
	v_and_b32_e32 v29, 0xffff0000, v122
	v_add_f32_e32 v117, 1.0, v117
	v_rcp_f32_e32 v128, v117
	v_mul_f32_e32 v117, 0xbfb8aa3b, v121
	v_exp_f32_e32 v117, v117
	v_pk_fma_f32 v[132:133], v[24:25], v[28:29], v[132:133]
	v_lshlrev_b32_e32 v24, 16, v134
	v_and_b32_e32 v25, 0xffff0000, v134
	v_pk_fma_f32 v[124:125], v[124:125], v[24:25], v[132:133]
	v_lshlrev_b32_e32 v132, 16, v118
	v_and_b32_e32 v133, 0xffff0000, v118
	v_add_f32_e32 v117, 1.0, v117
	s_waitcnt lgkmcnt(0)
	v_pk_fma_f32 v[0:1], v[0:1], v[132:133], v[124:125]
	v_rcp_f32_e32 v129, v117
	v_mul_f32_e32 v117, 0xbfb8aa3b, v0
	v_exp_f32_e32 v117, v117
	v_lshlrev_b32_e32 v130, 16, v131
	v_and_b32_e32 v131, 0xffff0000, v131
	v_pk_fma_f32 v[130:131], v[30:31], v[130:131], 0 op_sel_hi:[1,1,0]
	v_add_f32_e32 v117, 1.0, v117
	v_rcp_f32_e32 v124, v117
	v_mul_f32_e32 v117, 0xbfb8aa3b, v1
	v_exp_f32_e32 v117, v117
	v_lshlrev_b32_e32 v122, 16, v123
	v_and_b32_e32 v123, 0xffff0000, v123
	v_pk_fma_f32 v[122:123], v[26:27], v[122:123], v[130:131]
	v_lshlrev_b32_e32 v130, 16, v135
	v_and_b32_e32 v131, 0xffff0000, v135
	v_pk_fma_f32 v[122:123], v[126:127], v[130:131], v[122:123]
	v_lshlrev_b32_e32 v118, 16, v119
	v_and_b32_e32 v119, 0xffff0000, v119
	v_add_f32_e32 v117, 1.0, v117
	v_pk_fma_f32 v[2:3], v[2:3], v[118:119], v[122:123]
	v_rcp_f32_e32 v125, v117
	v_mul_f32_e32 v117, 0xbfb8aa3b, v2
	v_exp_f32_e32 v117, v117
	v_pk_mul_f32 v[32:33], v[32:33], v[34:35]
	v_pk_mul_f32 v[120:121], v[120:121], v[128:129]
	v_pk_mul_f32 v[34:35], v[32:33], v[32:33]
	v_add_f32_e32 v117, 1.0, v117
	v_rcp_f32_e32 v118, v117
	v_mul_f32_e32 v117, 0xbfb8aa3b, v3
	v_exp_f32_e32 v117, v117
	v_pk_mul_f32 v[128:129], v[120:121], v[120:121]
	v_pk_mul_f32 v[0:1], v[0:1], v[124:125]
	v_add_f32_e32 v117, 1.0, v117
	v_rcp_f32_e32 v119, v117
	v_add_f32_e32 v117, v34, v35
	v_add_f32_e32 v117, v128, v117
	v_pk_mul_f32 v[124:125], v[0:1], v[0:1]
	v_add_f32_e32 v117, v129, v117
	v_pk_mul_f32 v[2:3], v[2:3], v[118:119]
	v_add_f32_e32 v117, v124, v117
	v_pk_mul_f32 v[118:119], v[2:3], v[2:3]
	v_add_f32_e32 v117, v125, v117
	v_add_f32_e32 v117, v118, v117
	v_add_f32_e32 v117, v119, v117
	ds_bpermute_b32 v118, v37, v117
	s_waitcnt lgkmcnt(0)
	v_add_f32_e32 v117, v117, v118
	ds_bpermute_b32 v118, v38, v117
	s_waitcnt lgkmcnt(0)
	v_add_f32_e32 v117, v117, v118
	ds_bpermute_b32 v118, v39, v117
	s_waitcnt lgkmcnt(0)
	v_add_f32_e32 v117, v117, v118
	ds_bpermute_b32 v118, v40, v117
	s_and_saveexec_b64 s[22:23], vcc
	s_cbranch_execz .Ls1t2_745
	s_waitcnt lgkmcnt(0)
	v_add_f32_e32 v116, v117, v118
	v_add_f32_e32 v116, 0x358637bd, v116
	v_mul_f32_e32 v117, 0x4b800000, v116
	v_cmp_gt_f32_e32 vcc, s34, v116
	s_nop 1
	v_cndmask_b32_e32 v116, v116, v117, vcc
	v_rsq_f32_e32 v116, v116
	s_nop 0
	v_mul_f32_e32 v117, 0x45800000, v116
	v_cndmask_b32_e32 v116, v116, v117, vcc
.Ls1t2_745:
	s_or_b64 exec, exec, s[22:23]
	s_waitcnt lgkmcnt(0)
	v_pk_mul_f32 v[118:119], v[32:33], v[116:117] op_sel_hi:[1,0]
	v_pk_mul_f32 v[120:121], v[120:121], v[116:117] op_sel_hi:[1,0]
	v_pk_mul_f32 v[0:1], v[0:1], v[116:117] op_sel_hi:[1,0]
	v_cvt_pk_bf16_f32 v118, v118, v119
	v_cvt_pk_bf16_f32 v119, v120, v121
	v_cvt_pk_bf16_f32 v120, v0, v1
	v_pk_mul_f32 v[0:1], v[2:3], v[116:117] op_sel_hi:[1,0]
	v_cmp_eq_u32_e32 vcc, 1, v113
	v_cvt_pk_bf16_f32 v121, v0, v1
	v_mul_u32_u24_e32 v1, 0x110, v112
	v_cndmask_b32_e64 v0, v188, 0, vcc
	v_add_u32_e32 v0, 0, v0
	v_add3_u32 v0, v0, v1, v151
	ds_write_b128 v0, v[118:121]
	v_add_u32_e32 v0, 0x400, v111
	v_lshrrev_b32_e32 v113, 10, v0
	v_add_u32_e32 v0, 0x60, v218
	v_and_b32_e32 v112, 63, v0
	v_lshl_add_u32 v1, v113, 9, v36
	v_add_u32_e32 v0, s86, v112
	v_mov_b32_e32 v120, 0
	v_cmp_lt_i32_e32 vcc, -1, v0
	v_lshlrev_b32_e32 v56, 1, v1
	v_mov_b32_e32 v128, 0
	v_mov_b32_e32 v129, 0
	v_mov_b32_e32 v130, 0
	v_mov_b32_e32 v131, 0
	s_and_saveexec_b64 s[22:23], vcc
	v_add_u32_e32 v1, s41, v0
	v_mov_b64_e32 v[2:3], s[10:11]
	v_mad_u64_u32 v[2:3], vcc, v1, s25, v[2:3]
	v_lshl_add_u64 v[2:3], v[2:3], 0, v[56:57]
	global_load_dwordx4 v[128:131], v[2:3], off

; #define LAS __attribute__((address_space(3)))
; __device__ __forceinline__ float lo_bf(unsigned w) { return __uint_as_float(w << 16); }
; __device__ __forceinline__ float hi_bf(unsigned w) { return __uint_as_float(w & 0xffff0000u); }
; __device__ __forceinline__ unsigned pk2(float lo, float hi) { const f32x2_t v = {lo, hi}; const bf16x2_t b = __builtin_convertvector(v, bf16x2_t); return __builtin_bit_cast(unsigned, b); }
; __device__ __forceinline__ float silu_(float x) { return x * sigm(x); }
; __device__ __forceinline__ void dn_prep_item(const Args& a, LAS unsigned char* lds, int item, int tid, int wave, int lane, int& cwh, int next_item) {
;     ...
;     for (int r = 0; r < 6; ++r) { const int task = tid + NTHR * r, which = task >> 10, i = (task & 1023) >> 4, gq = task & 15;
;         const int col = 1024 + which * 512 + h * 128 + 8 * gq;
;         v4u xv[4];
; #pragma unroll
;         for (int jj = 0; jj < 4; ++jj) { const int pos = n * 64 + i - 3 + jj; xv[jj] = (v4u){0u, 0u, 0u, 0u};
;             if (pos >= 0) xv[jj] = *(const v4u*)(P + (size_t)(b * T + pos) * NIN + col); }
;         float o[8];
; #pragma unroll
;         for (int q = 0; q < 8; ++q) o[q] = 0.f;
; #pragma unroll
;         for (int jj = 0; jj < 4; ++jj) { const v4u v = xv[jj];
;             const f32x4 w0 = *(const LAS f32x4*)(cwl + (which * 4 + jj) * 128 + 8 * gq), w1 = *(const LAS f32x4*)(cwl + (which * 4 + jj) * 128 + 8 * gq + 4);
;             o[0] += w0[0] * lo_bf(v.x); o[1] += w0[1] * hi_bf(v.x); o[2] += w0[2] * lo_bf(v.y); o[3] += w0[3] * hi_bf(v.y);
;             o[4] += w1[0] * lo_bf(v.z); o[5] += w1[1] * hi_bf(v.z); o[6] += w1[2] * lo_bf(v.w); o[7] += w1[3] * hi_bf(v.w); }
;         float s = 0.f;
; #pragma unroll
;         for (int q = 0; q < 8; ++q) { o[q] = silu_(o[q]); s += o[q] * o[q]; }
;         s += __shfl_xor(s, 1); s += __shfl_xor(s, 2); s += __shfl_xor(s, 4); s += __shfl_xor(s, 8);
;         const float inv = which == 2 ? 1.0f : rsqrtf(s + EPS) * (which == 0 ? 0.08838834764831845f : 1.0f);
;         v4u w; w.x = pk2(o[0] * inv, o[1] * inv); w.y = pk2(o[2] * inv, o[3] * inv); w.z = pk2(o[4] * inv, o[5] * inv); w.w = pk2(o[6] * inv, o[7] * inv);
;         *(LAS v4u*)(lds + (which == 0 ? L_QS : which == 1 ? L_KH : L_V) + i * KS_ + 16 * gq) = w;
.Ls1t5_768:
	s_or_b64 exec, exec, s[22:23]
	v_or_b32_e32 v2, s39, v112
	v_mov_b64_e32 v[0:1], s[10:11]
	v_mad_u64_u32 v[0:1], s[22:23], v2, s25, v[0:1]
	v_lshl_add_u64 v[0:1], v[0:1], 0, v[56:57]
	global_load_dwordx4 v[116:119], v[0:1], off
	v_lshl_add_u32 v0, v43, 11, v150
	ds_read_b128 v[44:47], v0
	ds_read_b128 v[28:31], v0 offset:16
	ds_read_b128 v[72:75], v0 offset:512
	ds_read_b128 v[24:27], v0 offset:528
	ds_read_b128 v[76:79], v0 offset:1024
	ds_read_b128 v[12:15], v0 offset:1040
	ds_read_b128 v[80:83], v0 offset:1536
	ds_read_b128 v[0:3], v0 offset:1552
	s_waitcnt vmcnt(11)
	v_lshlrev_b32_e32 v32, 16, v16
	v_and_b32_e32 v33, 0xffff0000, v16
	s_waitcnt lgkmcnt(0)
	v_pk_fma_f32 v[32:33], v[44:45], v[32:33], 0 op_sel_hi:[1,1,0]
	s_waitcnt vmcnt(10)
	v_lshlrev_b32_e32 v34, 16, v8
	v_and_b32_e32 v35, 0xffff0000, v8
	v_pk_fma_f32 v[32:33], v[72:73], v[34:35], v[32:33]
	s_waitcnt vmcnt(9)
	v_lshlrev_b32_e32 v34, 16, v20
	v_and_b32_e32 v35, 0xffff0000, v20
	v_pk_fma_f32 v[32:33], v[76:77], v[34:35], v[32:33]
	v_lshlrev_b32_e32 v16, 16, v17
	v_and_b32_e32 v17, 0xffff0000, v17
	v_pk_fma_f32 v[16:17], v[46:47], v[16:17], 0 op_sel_hi:[1,1,0]
	v_lshlrev_b32_e32 v20, 16, v18
	v_cmp_ne_u32_e32 vcc, 2, v43
	s_waitcnt vmcnt(8)
	v_lshlrev_b32_e32 v34, 16, v4
	v_and_b32_e32 v35, 0xffff0000, v4
	v_pk_fma_f32 v[32:33], v[80:81], v[34:35], v[32:33]
	s_nop 0
	v_mul_f32_e32 v4, 0xbfb8aa3b, v32
	v_exp_f32_e32 v8, v4
	v_mov_b32_e32 v4, 1.0
	v_add_f32_e32 v8, 1.0, v8
	v_rcp_f32_e32 v34, v8
	v_mul_f32_e32 v8, 0xbfb8aa3b, v33
	v_exp_f32_e32 v8, v8
	s_nop 0
	v_add_f32_e32 v8, 1.0, v8
	v_rcp_f32_e32 v35, v8
	v_lshlrev_b32_e32 v8, 16, v9
	v_and_b32_e32 v9, 0xffff0000, v9
	v_pk_fma_f32 v[8:9], v[74:75], v[8:9], v[16:17]
	v_lshlrev_b32_e32 v16, 16, v21
	v_and_b32_e32 v17, 0xffff0000, v21
	v_pk_fma_f32 v[8:9], v[78:79], v[16:17], v[8:9]
	v_lshlrev_b32_e32 v16, 16, v5
	v_and_b32_e32 v17, 0xffff0000, v5
	v_pk_fma_f32 v[8:9], v[82:83], v[16:17], v[8:9]
	v_and_b32_e32 v21, 0xffff0000, v18
	v_mul_f32_e32 v5, 0xbfb8aa3b, v8
	v_exp_f32_e32 v5, v5
	v_pk_fma_f32 v[20:21], v[28:29], v[20:21], 0 op_sel_hi:[1,1,0]
	v_lshlrev_b32_e32 v28, 16, v10
	v_and_b32_e32 v29, 0xffff0000, v10
	v_add_f32_e32 v5, 1.0, v5
	v_rcp_f32_e32 v16, v5
	v_mul_f32_e32 v5, 0xbfb8aa3b, v9
	v_exp_f32_e32 v5, v5
	v_pk_fma_f32 v[20:21], v[24:25], v[28:29], v[20:21]
	v_lshlrev_b32_e32 v24, 16, v22
	v_and_b32_e32 v25, 0xffff0000, v22
	v_pk_fma_f32 v[12:13], v[12:13], v[24:25], v[20:21]
	v_lshlrev_b32_e32 v20, 16, v6
	v_and_b32_e32 v21, 0xffff0000, v6
	v_add_f32_e32 v5, 1.0, v5
	v_pk_fma_f32 v[0:1], v[0:1], v[20:21], v[12:13]
	v_rcp_f32_e32 v17, v5
	v_mul_f32_e32 v5, 0xbfb8aa3b, v0
	v_exp_f32_e32 v5, v5
	v_lshlrev_b32_e32 v18, 16, v19
	v_and_b32_e32 v19, 0xffff0000, v19
	v_pk_fma_f32 v[18:19], v[30:31], v[18:19], 0 op_sel_hi:[1,1,0]
	v_add_f32_e32 v5, 1.0, v5
	v_rcp_f32_e32 v12, v5
	v_mul_f32_e32 v5, 0xbfb8aa3b, v1
	v_exp_f32_e32 v5, v5
	v_lshlrev_b32_e32 v10, 16, v11
	v_and_b32_e32 v11, 0xffff0000, v11
	v_pk_fma_f32 v[10:11], v[26:27], v[10:11], v[18:19]
	v_lshlrev_b32_e32 v18, 16, v23
	v_and_b32_e32 v19, 0xffff0000, v23
	v_pk_fma_f32 v[10:11], v[14:15], v[18:19], v[10:11]
	v_lshlrev_b32_e32 v6, 16, v7
	v_and_b32_e32 v7, 0xffff0000, v7
	v_add_f32_e32 v5, 1.0, v5
	v_pk_fma_f32 v[2:3], v[2:3], v[6:7], v[10:11]
	v_rcp_f32_e32 v13, v5
	v_mul_f32_e32 v5, 0xbfb8aa3b, v2
	v_exp_f32_e32 v5, v5
	v_pk_mul_f32 v[32:33], v[32:33], v[34:35]
	v_pk_mul_f32 v[8:9], v[8:9], v[16:17]
	v_pk_mul_f32 v[34:35], v[32:33], v[32:33]
	v_add_f32_e32 v5, 1.0, v5
	v_rcp_f32_e32 v6, v5
	v_mul_f32_e32 v5, 0xbfb8aa3b, v3
	v_exp_f32_e32 v5, v5
	v_pk_mul_f32 v[16:17], v[8:9], v[8:9]
	v_pk_mul_f32 v[0:1], v[0:1], v[12:13]
	v_add_f32_e32 v5, 1.0, v5
	v_rcp_f32_e32 v7, v5
	v_add_f32_e32 v5, v34, v35
	v_add_f32_e32 v5, v16, v5
	v_pk_mul_f32 v[12:13], v[0:1], v[0:1]
	v_add_f32_e32 v5, v17, v5
	v_pk_mul_f32 v[2:3], v[2:3], v[6:7]
	v_add_f32_e32 v5, v12, v5
	v_pk_mul_f32 v[6:7], v[2:3], v[2:3]
	v_add_f32_e32 v5, v13, v5
	v_add_f32_e32 v5, v6, v5
	v_add_f32_e32 v5, v7, v5
	ds_bpermute_b32 v6, v37, v5
	s_waitcnt lgkmcnt(0)
	v_add_f32_e32 v5, v5, v6
	ds_bpermute_b32 v6, v38, v5
	s_waitcnt lgkmcnt(0)
	v_add_f32_e32 v5, v5, v6
	ds_bpermute_b32 v6, v39, v5
	s_waitcnt lgkmcnt(0)
	v_add_f32_e32 v5, v5, v6
	ds_bpermute_b32 v6, v40, v5
	s_and_saveexec_b64 s[22:23], vcc
	s_cbranch_execz .Ls1t3_754
	s_waitcnt lgkmcnt(0)
	v_add_f32_e32 v4, v5, v6
	v_add_f32_e32 v4, 0x358637bd, v4
	v_mul_f32_e32 v5, 0x4b800000, v4
	v_cmp_gt_f32_e32 vcc, s34, v4
	s_nop 1
	v_cndmask_b32_e32 v4, v4, v5, vcc
	v_rsq_f32_e32 v4, v4
	s_nop 0
	v_mul_f32_e32 v5, 0x45800000, v4
	v_cndmask_b32_e32 v4, v4, v5, vcc
	v_cmp_gt_u32_e32 vcc, s30, v111
	s_nop 1
	v_cndmask_b32_e32 v5, 1.0, v231, vcc
	v_mul_f32_e32 v4, v5, v4
; #define LAS __attribute__((address_space(3)))
; __device__ __forceinline__ float lo_bf(unsigned w) { return __uint_as_float(w << 16); }
; __device__ __forceinline__ float hi_bf(unsigned w) { return __uint_as_float(w & 0xffff0000u); }
; __device__ __forceinline__ unsigned pk2(float lo, float hi) { const f32x2_t v = {lo, hi}; const bf16x2_t b = __builtin_convertvector(v, bf16x2_t); return __builtin_bit_cast(unsigned, b); }
; __device__ __forceinline__ float silu_(float x) { return x * sigm(x); }
; __device__ __forceinline__ void dn_prep_item(const Args& a, LAS unsigned char* lds, int item, int tid, int wave, int lane, int& cwh, int next_item) {
;     ...
;     for (int r = 0; r < 6; ++r) { const int task = tid + NTHR * r, which = task >> 10, i = (task & 1023) >> 4, gq = task & 15;
;         const int col = 1024 + which * 512 + h * 128 + 8 * gq;
;         v4u xv[4];
; #pragma unroll
;         for (int jj = 0; jj < 4; ++jj) { const int pos = n * 64 + i - 3 + jj; xv[jj] = (v4u){0u, 0u, 0u, 0u};
;             if (pos >= 0) xv[jj] = *(const v4u*)(P + (size_t)(b * T + pos) * NIN + col); }
;         float o[8];
; #pragma unroll
;         for (int q = 0; q < 8; ++q) o[q] = 0.f;
; #pragma unroll
;         for (int jj = 0; jj < 4; ++jj) { const v4u v = xv[jj];
;             const f32x4 w0 = *(const LAS f32x4*)(cwl + (which * 4 + jj) * 128 + 8 * gq), w1 = *(const LAS f32x4*)(cwl + (which * 4 + jj) * 128 + 8 * gq + 4);
;             o[0] += w0[0] * lo_bf(v.x); o[1] += w0[1] * hi_bf(v.x); o[2] += w0[2] * lo_bf(v.y); o[3] += w0[3] * hi_bf(v.y);
;             o[4] += w1[0] * lo_bf(v.z); o[5] += w1[1] * hi_bf(v.z); o[6] += w1[2] * lo_bf(v.w); o[7] += w1[3] * hi_bf(v.w); }
;         float s = 0.f;
; #pragma unroll
;         for (int q = 0; q < 8; ++q) { o[q] = silu_(o[q]); s += o[q] * o[q]; }
;         s += __shfl_xor(s, 1); s += __shfl_xor(s, 2); s += __shfl_xor(s, 4); s += __shfl_xor(s, 8);
;         const float inv = which == 2 ? 1.0f : rsqrtf(s + EPS) * (which == 0 ? 0.08838834764831845f : 1.0f);
;         v4u w; w.x = pk2(o[0] * inv, o[1] * inv); w.y = pk2(o[2] * inv, o[3] * inv); w.z = pk2(o[4] * inv, o[5] * inv); w.w = pk2(o[6] * inv, o[7] * inv);
;         *(LAS v4u*)(lds + (which == 0 ? L_QS : which == 1 ? L_KH : L_V) + i * KS_ + 16 * gq) = w;
.Ls1t3_754:
	s_or_b64 exec, exec, s[22:23]
	v_pk_mul_f32 v[0:1], v[0:1], v[4:5] op_sel_hi:[1,0]
	v_cmp_eq_u32_e32 vcc, 1, v43
	v_cvt_pk_bf16_f32 v12, v0, v1
	v_pk_mul_f32 v[0:1], v[2:3], v[4:5] op_sel_hi:[1,0]
	s_waitcnt lgkmcnt(0)
	v_pk_mul_f32 v[6:7], v[32:33], v[4:5] op_sel_hi:[1,0]
	v_cvt_pk_bf16_f32 v13, v0, v1
	v_cndmask_b32_e64 v0, v188, 0, vcc
	v_cmp_lt_u32_e32 vcc, s31, v111
	v_cvt_pk_bf16_f32 v10, v6, v7
	v_pk_mul_f32 v[6:7], v[8:9], v[4:5] op_sel_hi:[1,0]
	v_cndmask_b32_e32 v0, v232, v0, vcc
	v_add_u32_e32 v0, 0, v0
	v_mul_u32_u24_e32 v1, 0x110, v42
	v_cvt_pk_bf16_f32 v11, v6, v7
	v_add3_u32 v0, v0, v1, v151
	ds_write_b128 v0, v[10:13]
	v_lshl_add_u32 v0, v110, 11, v150
	ds_read_b128 v[72:75], v0
	ds_read_b128 v[28:31], v0 offset:16
	ds_read_b128 v[76:79], v0 offset:512
	ds_read_b128 v[24:27], v0 offset:528
	ds_read_b128 v[80:83], v0 offset:1024
	ds_read_b128 v[96:99], v0 offset:1040
	ds_read_b128 v[84:87], v0 offset:1536
	ds_read_b128 v[0:3], v0 offset:1552
	s_waitcnt vmcnt(7)
	v_lshlrev_b32_e32 v32, 16, v100
	v_and_b32_e32 v33, 0xffff0000, v100
	s_waitcnt lgkmcnt(7)
	v_pk_fma_f32 v[32:33], v[72:73], v[32:33], 0 op_sel_hi:[1,1,0]
	s_waitcnt vmcnt(6)
	v_lshlrev_b32_e32 v34, 16, v92
	v_and_b32_e32 v35, 0xffff0000, v92
	s_waitcnt lgkmcnt(5)
	v_pk_fma_f32 v[32:33], v[76:77], v[34:35], v[32:33]
	s_waitcnt vmcnt(5)
	v_lshlrev_b32_e32 v34, 16, v104
	v_and_b32_e32 v35, 0xffff0000, v104
	s_waitcnt lgkmcnt(3)
	v_pk_fma_f32 v[32:33], v[80:81], v[34:35], v[32:33]
	v_lshlrev_b32_e32 v100, 16, v101
	v_and_b32_e32 v101, 0xffff0000, v101
	v_pk_fma_f32 v[100:101], v[74:75], v[100:101], 0 op_sel_hi:[1,1,0]
	v_lshlrev_b32_e32 v104, 16, v102
	v_cmp_ne_u32_e32 vcc, 2, v110
	s_waitcnt vmcnt(4)
	v_lshlrev_b32_e32 v34, 16, v88
	v_and_b32_e32 v35, 0xffff0000, v88
	s_waitcnt lgkmcnt(1)
	v_pk_fma_f32 v[32:33], v[84:85], v[34:35], v[32:33]
	s_nop 0
	v_mul_f32_e32 v88, 0xbfb8aa3b, v32
	v_exp_f32_e32 v92, v88
	v_mov_b32_e32 v88, 1.0
	v_add_f32_e32 v92, 1.0, v92
	v_rcp_f32_e32 v34, v92
	v_mul_f32_e32 v92, 0xbfb8aa3b, v33
	v_exp_f32_e32 v92, v92
	s_nop 0
	v_add_f32_e32 v92, 1.0, v92
	v_rcp_f32_e32 v35, v92
	v_lshlrev_b32_e32 v92, 16, v93
	v_and_b32_e32 v93, 0xffff0000, v93
	v_pk_fma_f32 v[92:93], v[78:79], v[92:93], v[100:101]
	v_lshlrev_b32_e32 v100, 16, v105
	v_and_b32_e32 v101, 0xffff0000, v105
	v_pk_fma_f32 v[92:93], v[82:83], v[100:101], v[92:93]
	v_lshlrev_b32_e32 v100, 16, v89
	v_and_b32_e32 v101, 0xffff0000, v89
	v_pk_fma_f32 v[92:93], v[86:87], v[100:101], v[92:93]
	v_and_b32_e32 v105, 0xffff0000, v102
	v_mul_f32_e32 v89, 0xbfb8aa3b, v92
	v_exp_f32_e32 v89, v89
	v_pk_fma_f32 v[104:105], v[28:29], v[104:105], 0 op_sel_hi:[1,1,0]
	v_lshlrev_b32_e32 v28, 16, v94
	v_and_b32_e32 v29, 0xffff0000, v94
	v_add_f32_e32 v89, 1.0, v89
	v_rcp_f32_e32 v100, v89
	v_mul_f32_e32 v89, 0xbfb8aa3b, v93
	v_exp_f32_e32 v89, v89
	v_pk_fma_f32 v[104:105], v[24:25], v[28:29], v[104:105]
	v_lshlrev_b32_e32 v24, 16, v106
	v_and_b32_e32 v25, 0xffff0000, v106
	v_pk_fma_f32 v[96:97], v[96:97], v[24:25], v[104:105]
	v_lshlrev_b32_e32 v104, 16, v90
	v_and_b32_e32 v105, 0xffff0000, v90
	v_add_f32_e32 v89, 1.0, v89
	s_waitcnt lgkmcnt(0)
	v_pk_fma_f32 v[0:1], v[0:1], v[104:105], v[96:97]
	v_rcp_f32_e32 v101, v89
	v_mul_f32_e32 v89, 0xbfb8aa3b, v0
	v_exp_f32_e32 v89, v89
	v_lshlrev_b32_e32 v102, 16, v103
	v_and_b32_e32 v103, 0xffff0000, v103
	v_pk_fma_f32 v[102:103], v[30:31], v[102:103], 0 op_sel_hi:[1,1,0]
	v_add_f32_e32 v89, 1.0, v89
	v_rcp_f32_e32 v96, v89
	v_mul_f32_e32 v89, 0xbfb8aa3b, v1
	v_exp_f32_e32 v89, v89
	v_lshlrev_b32_e32 v94, 16, v95
	v_and_b32_e32 v95, 0xffff0000, v95
	v_pk_fma_f32 v[94:95], v[26:27], v[94:95], v[102:103]
	v_lshlrev_b32_e32 v102, 16, v107
	v_and_b32_e32 v103, 0xffff0000, v107
	v_pk_fma_f32 v[94:95], v[98:99], v[102:103], v[94:95]
	v_lshlrev_b32_e32 v90, 16, v91
	v_and_b32_e32 v91, 0xffff0000, v91
	v_add_f32_e32 v89, 1.0, v89
	v_pk_fma_f32 v[2:3], v[2:3], v[90:91], v[94:95]
	v_rcp_f32_e32 v97, v89
	v_mul_f32_e32 v89, 0xbfb8aa3b, v2
	v_exp_f32_e32 v89, v89
	v_pk_mul_f32 v[32:33], v[32:33], v[34:35]
	v_pk_mul_f32 v[92:93], v[92:93], v[100:101]
	v_pk_mul_f32 v[34:35], v[32:33], v[32:33]
	v_add_f32_e32 v89, 1.0, v89
	v_rcp_f32_e32 v90, v89
	v_mul_f32_e32 v89, 0xbfb8aa3b, v3
	v_exp_f32_e32 v89, v89
	v_pk_mul_f32 v[100:101], v[92:93], v[92:93]
	v_pk_mul_f32 v[0:1], v[0:1], v[96:97]
	v_add_f32_e32 v89, 1.0, v89
	v_rcp_f32_e32 v91, v89
	v_add_f32_e32 v89, v34, v35
	v_add_f32_e32 v89, v100, v89
	v_pk_mul_f32 v[96:97], v[0:1], v[0:1]
	v_add_f32_e32 v89, v101, v89
	v_pk_mul_f32 v[2:3], v[2:3], v[90:91]
	v_add_f32_e32 v89, v96, v89
	v_pk_mul_f32 v[90:91], v[2:3], v[2:3]
	v_add_f32_e32 v89, v97, v89
	v_add_f32_e32 v89, v90, v89
	v_add_f32_e32 v89, v91, v89
	ds_bpermute_b32 v90, v37, v89
	s_waitcnt lgkmcnt(0)
	v_add_f32_e32 v89, v89, v90
	ds_bpermute_b32 v90, v38, v89
	s_waitcnt lgkmcnt(0)
	v_add_f32_e32 v89, v89, v90
	ds_bpermute_b32 v90, v39, v89
	s_waitcnt lgkmcnt(0)
	v_add_f32_e32 v89, v89, v90
	ds_bpermute_b32 v90, v40, v89
	s_and_saveexec_b64 s[22:23], vcc
	s_cbranch_execz .Ls1t4_762
	s_waitcnt lgkmcnt(0)
	v_add_f32_e32 v88, v89, v90
	v_add_f32_e32 v88, 0x358637bd, v88
	v_mul_f32_e32 v89, 0x4b800000, v88
	v_cmp_gt_f32_e32 vcc, s34, v88
	s_nop 1
	v_cndmask_b32_e32 v88, v88, v89, vcc
	v_rsq_f32_e32 v88, v88
	s_nop 0
	v_mul_f32_e32 v89, 0x45800000, v88
	v_cndmask_b32_e32 v88, v88, v89, vcc
	v_cmp_gt_u32_e32 vcc, s30, v108
	s_nop 1
	v_cndmask_b32_e32 v89, 1.0, v231, vcc
	v_mul_f32_e32 v88, v89, v88
; #define LAS __attribute__((address_space(3)))
; __device__ __forceinline__ float lo_bf(unsigned w) { return __uint_as_float(w << 16); }
; __device__ __forceinline__ float hi_bf(unsigned w) { return __uint_as_float(w & 0xffff0000u); }
; __device__ __forceinline__ unsigned pk2(float lo, float hi) { const f32x2_t v = {lo, hi}; const bf16x2_t b = __builtin_convertvector(v, bf16x2_t); return __builtin_bit_cast(unsigned, b); }
; __device__ __forceinline__ float silu_(float x) { return x * sigm(x); }
; __device__ __forceinline__ void dn_prep_item(const Args& a, LAS unsigned char* lds, int item, int tid, int wave, int lane, int& cwh, int next_item) {
;     ...
; #pragma unroll 3
;     for (int r = 0; r < 6; ++r) { const int task = tid + NTHR * r, which = task >> 10, i = (task & 1023) >> 4, gq = task & 15;
;         const int col = 1024 + which * 512 + h * 128 + 8 * gq;
;         v4u xv[4];
; #pragma unroll
;         for (int jj = 0; jj < 4; ++jj) { const int pos = n * 64 + i - 3 + jj; xv[jj] = (v4u){0u, 0u, 0u, 0u};
;             if (pos >= 0) xv[jj] = *(const v4u*)(P + (size_t)(b * T + pos) * NIN + col); }
;         float o[8];
; #pragma unroll
;         for (int q = 0; q < 8; ++q) o[q] = 0.f;
; #pragma unroll
;         for (int jj = 0; jj < 4; ++jj) { const v4u v = xv[jj];
;             const f32x4 w0 = *(const LAS f32x4*)(cwl + (which * 4 + jj) * 128 + 8 * gq), w1 = *(const LAS f32x4*)(cwl + (which * 4 + jj) * 128 + 8 * gq + 4);
;             o[0] += w0[0] * lo_bf(v.x); o[1] += w0[1] * hi_bf(v.x); o[2] += w0[2] * lo_bf(v.y); o[3] += w0[3] * hi_bf(v.y);
;             o[4] += w1[0] * lo_bf(v.z); o[5] += w1[1] * hi_bf(v.z); o[6] += w1[2] * lo_bf(v.w); o[7] += w1[3] * hi_bf(v.w); }
;         float s = 0.f;
; #pragma unroll
;         for (int q = 0; q < 8; ++q) { o[q] = silu_(o[q]); s += o[q] * o[q]; }
;         s += __shfl_xor(s, 1); s += __shfl_xor(s, 2); s += __shfl_xor(s, 4); s += __shfl_xor(s, 8);
;         const float inv = which == 2 ? 1.0f : rsqrtf(s + EPS) * (which == 0 ? 0.08838834764831845f : 1.0f);
;         v4u w; w.x = pk2(o[0] * inv, o[1] * inv); w.y = pk2(o[2] * inv, o[3] * inv); w.z = pk2(o[4] * inv, o[5] * inv); w.w = pk2(o[6] * inv, o[7] * inv);
;         *(LAS v4u*)(lds + (which == 0 ? L_QS : which == 1 ? L_KH : L_V) + i * KS_ + 16 * gq) = w;
;     }
.Ls1t4_762:
	s_or_b64 exec, exec, s[22:23]
	v_pk_mul_f32 v[0:1], v[0:1], v[88:89] op_sel_hi:[1,0]
	v_cmp_eq_u32_e32 vcc, 1, v110
	v_cvt_pk_bf16_f32 v96, v0, v1
	v_pk_mul_f32 v[0:1], v[2:3], v[88:89] op_sel_hi:[1,0]
	s_waitcnt lgkmcnt(0)
	v_pk_mul_f32 v[90:91], v[32:33], v[88:89] op_sel_hi:[1,0]
	v_cvt_pk_bf16_f32 v97, v0, v1
	v_cndmask_b32_e64 v0, v188, 0, vcc
	v_cmp_lt_u32_e32 vcc, s31, v108
	v_cvt_pk_bf16_f32 v94, v90, v91
	v_pk_mul_f32 v[90:91], v[92:93], v[88:89] op_sel_hi:[1,0]
	v_cndmask_b32_e32 v0, v232, v0, vcc
	v_add_u32_e32 v0, 0, v0
	v_mul_u32_u24_e32 v1, 0x110, v109
	v_cvt_pk_bf16_f32 v95, v90, v91
	v_add3_u32 v0, v0, v1, v151
	ds_write_b128 v0, v[94:97]
	v_lshl_add_u32 v0, v113, 11, v150
	ds_read_b128 v[44:47], v0
	ds_read_b128 v[28:31], v0 offset:16
	ds_read_b128 v[72:75], v0 offset:512
	ds_read_b128 v[24:27], v0 offset:528
	ds_read_b128 v[76:79], v0 offset:1024
	ds_read_b128 v[124:127], v0 offset:1040
	ds_read_b128 v[80:83], v0 offset:1536
	ds_read_b128 v[0:3], v0 offset:1552
	s_waitcnt vmcnt(3)
	v_lshlrev_b32_e32 v32, 16, v128
	v_and_b32_e32 v33, 0xffff0000, v128
	s_waitcnt lgkmcnt(7)
	v_pk_fma_f32 v[32:33], v[44:45], v[32:33], 0 op_sel_hi:[1,1,0]
	s_waitcnt vmcnt(2)
	v_lshlrev_b32_e32 v34, 16, v120
	v_and_b32_e32 v35, 0xffff0000, v120
	s_waitcnt lgkmcnt(5)
	v_pk_fma_f32 v[32:33], v[72:73], v[34:35], v[32:33]
	s_waitcnt vmcnt(1)
	v_lshlrev_b32_e32 v34, 16, v132
	v_and_b32_e32 v35, 0xffff0000, v132
	s_waitcnt lgkmcnt(3)
	v_pk_fma_f32 v[32:33], v[76:77], v[34:35], v[32:33]
	v_lshlrev_b32_e32 v128, 16, v129
	v_and_b32_e32 v129, 0xffff0000, v129
	v_pk_fma_f32 v[128:129], v[46:47], v[128:129], 0 op_sel_hi:[1,1,0]
	v_lshlrev_b32_e32 v132, 16, v130
	v_cmp_ne_u32_e32 vcc, 2, v113
	s_waitcnt vmcnt(0)
	v_lshlrev_b32_e32 v34, 16, v116
	v_and_b32_e32 v35, 0xffff0000, v116
	s_waitcnt lgkmcnt(1)
	v_pk_fma_f32 v[32:33], v[80:81], v[34:35], v[32:33]
	s_nop 0
	v_mul_f32_e32 v116, 0xbfb8aa3b, v32
	v_exp_f32_e32 v120, v116
	v_mov_b32_e32 v116, 1.0
	v_add_f32_e32 v120, 1.0, v120
	v_rcp_f32_e32 v34, v120
	v_mul_f32_e32 v120, 0xbfb8aa3b, v33
	v_exp_f32_e32 v120, v120
	s_nop 0
	v_add_f32_e32 v120, 1.0, v120
	v_rcp_f32_e32 v35, v120
	v_lshlrev_b32_e32 v120, 16, v121
	v_and_b32_e32 v121, 0xffff0000, v121
	v_pk_fma_f32 v[120:121], v[74:75], v[120:121], v[128:129]
	v_lshlrev_b32_e32 v128, 16, v133
	v_and_b32_e32 v129, 0xffff0000, v133
	v_pk_fma_f32 v[120:121], v[78:79], v[128:129], v[120:121]
	v_lshlrev_b32_e32 v128, 16, v117
	v_and_b32_e32 v129, 0xffff0000, v117
	v_pk_fma_f32 v[120:121], v[82:83], v[128:129], v[120:121]
	v_and_b32_e32 v133, 0xffff0000, v130
	v_mul_f32_e32 v117, 0xbfb8aa3b, v120
	v_exp_f32_e32 v117, v117
	v_pk_fma_f32 v[132:133], v[28:29], v[132:133], 0 op_sel_hi:[1,1,0]
	v_lshlrev_b32_e32 v28, 16, v122
	v_and_b32_e32 v29, 0xffff0000, v122
	v_add_f32_e32 v117, 1.0, v117
	v_rcp_f32_e32 v128, v117
	v_mul_f32_e32 v117, 0xbfb8aa3b, v121
	v_exp_f32_e32 v117, v117
	v_pk_fma_f32 v[132:133], v[24:25], v[28:29], v[132:133]
	v_lshlrev_b32_e32 v24, 16, v134
	v_and_b32_e32 v25, 0xffff0000, v134
	v_pk_fma_f32 v[124:125], v[124:125], v[24:25], v[132:133]
	v_lshlrev_b32_e32 v132, 16, v118
	v_and_b32_e32 v133, 0xffff0000, v118
	v_add_f32_e32 v117, 1.0, v117
	s_waitcnt lgkmcnt(0)
	v_pk_fma_f32 v[0:1], v[0:1], v[132:133], v[124:125]
	v_rcp_f32_e32 v129, v117
	v_mul_f32_e32 v117, 0xbfb8aa3b, v0
	v_exp_f32_e32 v117, v117
	v_lshlrev_b32_e32 v130, 16, v131
	v_and_b32_e32 v131, 0xffff0000, v131
	v_pk_fma_f32 v[130:131], v[30:31], v[130:131], 0 op_sel_hi:[1,1,0]
	v_add_f32_e32 v117, 1.0, v117
	v_rcp_f32_e32 v124, v117
	v_mul_f32_e32 v117, 0xbfb8aa3b, v1
	v_exp_f32_e32 v117, v117
	v_lshlrev_b32_e32 v122, 16, v123
	v_and_b32_e32 v123, 0xffff0000, v123
	v_pk_fma_f32 v[122:123], v[26:27], v[122:123], v[130:131]
	v_lshlrev_b32_e32 v130, 16, v135
	v_and_b32_e32 v131, 0xffff0000, v135
	v_pk_fma_f32 v[122:123], v[126:127], v[130:131], v[122:123]
	v_lshlrev_b32_e32 v118, 16, v119
	v_and_b32_e32 v119, 0xffff0000, v119
	v_add_f32_e32 v117, 1.0, v117
	v_pk_fma_f32 v[2:3], v[2:3], v[118:119], v[122:123]
	v_rcp_f32_e32 v125, v117
	v_mul_f32_e32 v117, 0xbfb8aa3b, v2
	v_exp_f32_e32 v117, v117
	v_pk_mul_f32 v[32:33], v[32:33], v[34:35]
	v_pk_mul_f32 v[120:121], v[120:121], v[128:129]
	v_pk_mul_f32 v[34:35], v[32:33], v[32:33]
	v_add_f32_e32 v117, 1.0, v117
	v_rcp_f32_e32 v118, v117
	v_mul_f32_e32 v117, 0xbfb8aa3b, v3
	v_exp_f32_e32 v117, v117
	v_pk_mul_f32 v[128:129], v[120:121], v[120:121]
	v_pk_mul_f32 v[0:1], v[0:1], v[124:125]
	v_add_f32_e32 v117, 1.0, v117
	v_rcp_f32_e32 v119, v117
	v_add_f32_e32 v117, v34, v35
	v_add_f32_e32 v117, v128, v117
	v_pk_mul_f32 v[124:125], v[0:1], v[0:1]
	v_add_f32_e32 v117, v129, v117
	v_pk_mul_f32 v[2:3], v[2:3], v[118:119]
	v_add_f32_e32 v117, v124, v117
	v_pk_mul_f32 v[118:119], v[2:3], v[2:3]
	v_add_f32_e32 v117, v125, v117
	v_add_f32_e32 v117, v118, v117
	v_add_f32_e32 v117, v119, v117
	ds_bpermute_b32 v118, v37, v117
	s_waitcnt lgkmcnt(0)
	v_add_f32_e32 v117, v117, v118
	ds_bpermute_b32 v118, v38, v117
	s_waitcnt lgkmcnt(0)
	v_add_f32_e32 v117, v117, v118
	ds_bpermute_b32 v118, v39, v117
	s_waitcnt lgkmcnt(0)
	v_add_f32_e32 v117, v117, v118
	ds_bpermute_b32 v118, v40, v117
	s_and_saveexec_b64 s[22:23], vcc
	s_cbranch_execz .Ls1t5_745
	s_waitcnt lgkmcnt(0)
	v_add_f32_e32 v116, v117, v118
	v_add_f32_e32 v116, 0x358637bd, v116
	v_mul_f32_e32 v117, 0x4b800000, v116
	v_cmp_gt_f32_e32 vcc, s34, v116
	s_nop 1
	v_cndmask_b32_e32 v116, v116, v117, vcc
	v_rsq_f32_e32 v116, v116
	s_nop 0
	v_mul_f32_e32 v117, 0x45800000, v116
	v_cndmask_b32_e32 v116, v116, v117, vcc
.Ls1t5_745:
	s_or_b64 exec, exec, s[22:23]
	s_waitcnt lgkmcnt(0)
	v_pk_mul_f32 v[118:119], v[32:33], v[116:117] op_sel_hi:[1,0]
	v_pk_mul_f32 v[120:121], v[120:121], v[116:117] op_sel_hi:[1,0]
	v_pk_mul_f32 v[0:1], v[0:1], v[116:117] op_sel_hi:[1,0]
	v_cvt_pk_bf16_f32 v118, v118, v119
	v_cvt_pk_bf16_f32 v119, v120, v121
	v_cvt_pk_bf16_f32 v120, v0, v1
	v_pk_mul_f32 v[0:1], v[2:3], v[116:117] op_sel_hi:[1,0]
	v_cmp_eq_u32_e32 vcc, 1, v113
	v_cvt_pk_bf16_f32 v121, v0, v1
	v_mul_u32_u24_e32 v1, 0x110, v112
	v_cndmask_b32_e64 v0, v188, 0, vcc
	v_add_u32_e32 v0, 0, v0
	v_add3_u32 v0, v0, v1, v151
	ds_write_b128 v0, v[118:121]
